# sample-path Hyena filters produced once at the end of phase 2 (32-row MFMA, all rows used) into ws, conv units copy their 64 KiB image with LDS-DMA
# speedup vs baseline: 1.0296x; 1.0059x over previous
.LBB0_224:
	s_waitcnt vmcnt(0)
	v_readlane_b32 s0, v240, 22
	v_readlane_b32 s1, v240, 23
	s_barrier
	s_load_dwordx2 s[72:73], s[0:1], 0x98
	s_load_dwordx2 s[76:77], s[0:1], 0xa0
	v_and_b32_e32 v2, 63, v1
	v_and_b32_e32 v3, 31, v2
	v_lshrrev_b32_e32 v4, 5, v2
	v_lshrrev_b32_e32 v6, 6, v1
	v_mov_b32_e32 v82, 0
	s_mov_b32 s61, 0x447fc000
	v_lshlrev_b32_e32 v81, 7, v3
	v_readfirstlane_b32 s92, v6
	v_lshl_add_u32 v81, v4, 4, v81
	v_cmp_eq_u32_e64 s[14:15], 1, v4
	s_mov_b32 s93, s2
.Lpf_item:
	s_cmpk_gt_u32 s93, 0xff
	s_cbranch_scc1 .Lpf_end
	s_lshr_b32 s94, s93, 5
	s_lshl_b32 s94, s94, 3
	s_add_i32 s94, s94, s92
	s_and_b32 s95, s93, 31
	s_lshl_b32 s96, s94, 4
	v_bfe_u32 v7, v3, 2, 1
	v_lshrrev_b32_e32 v8, 3, v3
	v_and_b32_e32 v9, 3, v3
	v_lshlrev_b32_e32 v7, 10, v7
	v_lshl_add_u32 v7, v8, 2, v7
	v_add_u32_e32 v7, v7, v9
	v_add_u32_e32 v7, s96, v7
	v_lshlrev_b32_e32 v7, 2, v7
	v_lshl_add_u32 v80, v4, 16, v7
	s_waitcnt lgkmcnt(0)
	s_lshl_b32 s55, s96, 2
	s_add_u32 s90, s76, s55
	s_addc_u32 s91, s77, 0
	global_load_dwordx4 v[48:51], v82, s[90:91]
	global_load_dwordx4 v[52:55], v82, s[90:91] offset:16
	global_load_dwordx4 v[56:59], v82, s[90:91] offset:32
	global_load_dwordx4 v[66:69], v82, s[90:91] offset:48
	global_load_dword v84, v80, s[72:73]
	s_add_u32 s90, s72, 0x2000
	s_addc_u32 s91, s73, 0
	global_load_dword v85, v80, s[90:91]
	s_add_u32 s90, s72, 0x4000
	s_addc_u32 s91, s73, 0
	global_load_dword v86, v80, s[90:91]
	s_add_u32 s90, s72, 0x6000
	s_addc_u32 s91, s73, 0
	global_load_dword v87, v80, s[90:91]
	s_add_u32 s90, s72, 0x8000
	s_addc_u32 s91, s73, 0
	global_load_dword v88, v80, s[90:91]
	s_add_u32 s90, s72, 0xa000
	s_addc_u32 s91, s73, 0
	global_load_dword v89, v80, s[90:91]
	s_add_u32 s90, s72, 0xc000
	s_addc_u32 s91, s73, 0
	global_load_dword v90, v80, s[90:91]
	s_add_u32 s90, s72, 0xe000
	s_addc_u32 s91, s73, 0
	global_load_dword v91, v80, s[90:91]
	s_add_u32 s90, s72, 0x20000
	s_addc_u32 s91, s73, 0
	global_load_dword v92, v80, s[90:91]
	s_add_u32 s90, s72, 0x22000
	s_addc_u32 s91, s73, 0
	global_load_dword v93, v80, s[90:91]
	s_add_u32 s90, s72, 0x24000
	s_addc_u32 s91, s73, 0
	global_load_dword v94, v80, s[90:91]
	s_add_u32 s90, s72, 0x26000
	s_addc_u32 s91, s73, 0
	global_load_dword v95, v80, s[90:91]
	s_add_u32 s90, s72, 0x28000
	s_addc_u32 s91, s73, 0
	global_load_dword v96, v80, s[90:91]
	s_add_u32 s90, s72, 0x2a000
	s_addc_u32 s91, s73, 0
	global_load_dword v97, v80, s[90:91]
	s_add_u32 s90, s72, 0x2c000
	s_addc_u32 s91, s73, 0
	global_load_dword v98, v80, s[90:91]
	s_add_u32 s90, s72, 0x2e000
	s_addc_u32 s91, s73, 0
	global_load_dword v99, v80, s[90:91]
	s_add_u32 s90, s72, 0x40000
	s_addc_u32 s91, s73, 0
	global_load_dword v100, v80, s[90:91]
	s_add_u32 s90, s72, 0x42000
	s_addc_u32 s91, s73, 0
	global_load_dword v101, v80, s[90:91]
	s_add_u32 s90, s72, 0x44000
	s_addc_u32 s91, s73, 0
	global_load_dword v102, v80, s[90:91]
	s_add_u32 s90, s72, 0x46000
	s_addc_u32 s91, s73, 0
	global_load_dword v103, v80, s[90:91]
	s_add_u32 s90, s72, 0x48000
	s_addc_u32 s91, s73, 0
	global_load_dword v104, v80, s[90:91]
	s_add_u32 s90, s72, 0x4a000
	s_addc_u32 s91, s73, 0
	global_load_dword v105, v80, s[90:91]
	s_add_u32 s90, s72, 0x4c000
	s_addc_u32 s91, s73, 0
	global_load_dword v106, v80, s[90:91]
	s_add_u32 s90, s72, 0x4e000
	s_addc_u32 s91, s73, 0
	global_load_dword v107, v80, s[90:91]
	s_add_u32 s90, s72, 0x60000
	s_addc_u32 s91, s73, 0
	global_load_dword v108, v80, s[90:91]
	s_add_u32 s90, s72, 0x62000
	s_addc_u32 s91, s73, 0
	global_load_dword v109, v80, s[90:91]
	s_add_u32 s90, s72, 0x64000
	s_addc_u32 s91, s73, 0
	global_load_dword v110, v80, s[90:91]
	s_add_u32 s90, s72, 0x66000
	s_addc_u32 s91, s73, 0
	global_load_dword v111, v80, s[90:91]
	s_add_u32 s90, s72, 0x68000
	s_addc_u32 s91, s73, 0
	global_load_dword v76, v80, s[90:91]
	s_add_u32 s90, s72, 0x6a000
	s_addc_u32 s91, s73, 0
	global_load_dword v77, v80, s[90:91]
	s_add_u32 s90, s72, 0x6c000
	s_addc_u32 s91, s73, 0
	global_load_dword v78, v80, s[90:91]
	s_add_u32 s90, s72, 0x6e000
	s_addc_u32 s91, s73, 0
	global_load_dword v79, v80, s[90:91]
	s_lshl_b32 s55, s95, 14
	s_add_u32 s78, s66, 0x1a80000
	s_addc_u32 s79, s67, 0
	s_add_u32 s78, s78, s55
	s_addc_u32 s79, s79, 0
	s_add_u32 s80, s78, 0x80000
	s_addc_u32 s81, s79, 0
	global_load_dwordx4 v[112:115], v81, s[78:79]
	global_load_dwordx4 v[116:119], v81, s[78:79] offset:32
	global_load_dwordx4 v[120:123], v81, s[78:79] offset:64
	global_load_dwordx4 v[124:127], v81, s[78:79] offset:96
	global_load_dwordx4 v[128:131], v81, s[80:81]
	global_load_dwordx4 v[132:135], v81, s[80:81] offset:32
	global_load_dwordx4 v[136:139], v81, s[80:81] offset:64
	global_load_dwordx4 v[140:143], v81, s[80:81] offset:96
	s_add_u32 s78, s78, 0x1000
	s_addc_u32 s79, s79, 0
	s_add_u32 s80, s80, 0x1000
	s_addc_u32 s81, s81, 0
	global_load_dwordx4 v[144:147], v81, s[78:79]
	global_load_dwordx4 v[148:151], v81, s[78:79] offset:32
	global_load_dwordx4 v[152:155], v81, s[78:79] offset:64
	global_load_dwordx4 v[156:159], v81, s[78:79] offset:96
	global_load_dwordx4 v[160:163], v81, s[80:81]
	global_load_dwordx4 v[164:167], v81, s[80:81] offset:32
	global_load_dwordx4 v[168:171], v81, s[80:81] offset:64
	global_load_dwordx4 v[172:175], v81, s[80:81] offset:96
	s_add_u32 s78, s78, 0x1000
	s_addc_u32 s79, s79, 0
	s_add_u32 s80, s80, 0x1000
	s_addc_u32 s81, s81, 0
	global_load_dwordx4 v[176:179], v81, s[78:79]
	global_load_dwordx4 v[180:183], v81, s[78:79] offset:32
	global_load_dwordx4 v[184:187], v81, s[78:79] offset:64
	global_load_dwordx4 v[188:191], v81, s[78:79] offset:96
	global_load_dwordx4 v[192:195], v81, s[80:81]
	global_load_dwordx4 v[196:199], v81, s[80:81] offset:32
	global_load_dwordx4 v[200:203], v81, s[80:81] offset:64
	global_load_dwordx4 v[204:207], v81, s[80:81] offset:96
	s_add_u32 s78, s78, 0x1000
	s_addc_u32 s79, s79, 0
	s_add_u32 s80, s80, 0x1000
	s_addc_u32 s81, s81, 0
	global_load_dwordx4 v[208:211], v81, s[78:79]
	global_load_dwordx4 v[212:215], v81, s[78:79] offset:32
	global_load_dwordx4 v[216:219], v81, s[78:79] offset:64
	global_load_dwordx4 v[220:223], v81, s[78:79] offset:96
	global_load_dwordx4 v[224:227], v81, s[80:81]
	global_load_dwordx4 v[228:231], v81, s[80:81] offset:32
	global_load_dwordx4 v[232:235], v81, s[80:81] offset:64
	global_load_dwordx4 v[236:239], v81, s[80:81] offset:96
	s_lshl_b32 s55, s96, 14
	s_add_u32 s84, s66, 0x9c00000
	s_addc_u32 s85, s67, 0
	s_add_u32 s84, s84, s55
	s_addc_u32 s85, s85, 0
	v_and_b32_e32 v6, 15, v2
	v_add_u32_e32 v6, s96, v6
	v_cvt_f32_u32_e32 v6, v6
	v_div_scale_f32 v7, s[16:17], s61, s61, v6
	v_rcp_f32_e32 v8, v7
	v_div_scale_f32 v9, vcc, v6, s61, v6
	v_fma_f32 v10, -v7, v8, 1.0
	v_fmac_f32_e32 v8, v10, v8
	v_mul_f32_e32 v10, v9, v8
	v_fma_f32 v11, -v7, v10, v9
	v_fmac_f32_e32 v10, v11, v8
	v_fma_f32 v7, -v7, v10, v9
	s_nop 1
	v_div_fmas_f32 v7, v7, v8, v10
	v_div_fixup_f32 v6, v7, s61, v6
	v_mov_b32_e32 v7, 0xc0447cbd
	v_fmamk_f32 v6, v6, 0xc1447cbd, v7
	v_and_b32_e32 v6, 0x7fffffff, v6
	s_nop 0
	v_readlane_b32 s6, v6, 0
	v_readlane_b32 s7, v6, 1
	v_readlane_b32 s10, v6, 2
	v_readlane_b32 s11, v6, 3
	v_readlane_b32 s24, v6, 4
	v_readlane_b32 s26, v6, 5
	v_readlane_b32 s32, v6, 6
	v_readlane_b32 s35, v6, 7
	v_readlane_b32 s41, v6, 8
	v_readlane_b32 s44, v6, 9
	v_readlane_b32 s45, v6, 10
	v_readlane_b32 s47, v6, 11
	v_readlane_b32 s48, v6, 12
	v_readlane_b32 s49, v6, 13
	v_readlane_b32 s52, v6, 14
	v_readlane_b32 s53, v6, 15
	s_waitcnt vmcnt(32)
	v_cvt_pk_bf16_f32 v6, v84, v85
	v_lshlrev_b32_e32 v12, 16, v6
	v_and_b32_e32 v13, 0xffff0000, v6
	v_sub_f32_e32 v84, v84, v12
	v_sub_f32_e32 v85, v85, v13
	v_cvt_pk_bf16_f32 v70, v84, v85
	v_cvt_pk_bf16_f32 v7, v86, v87
	v_lshlrev_b32_e32 v12, 16, v7
	v_and_b32_e32 v13, 0xffff0000, v7
	v_sub_f32_e32 v86, v86, v12
	v_sub_f32_e32 v87, v87, v13
	v_cvt_pk_bf16_f32 v71, v86, v87
	v_cvt_pk_bf16_f32 v8, v88, v89
	v_lshlrev_b32_e32 v12, 16, v8
	v_and_b32_e32 v13, 0xffff0000, v8
	v_sub_f32_e32 v88, v88, v12
	v_sub_f32_e32 v89, v89, v13
	v_cvt_pk_bf16_f32 v72, v88, v89
	v_cvt_pk_bf16_f32 v9, v90, v91
	v_lshlrev_b32_e32 v12, 16, v9
	v_and_b32_e32 v13, 0xffff0000, v9
	v_sub_f32_e32 v90, v90, v12
	v_sub_f32_e32 v91, v91, v13
	v_cvt_pk_bf16_f32 v73, v90, v91
	v_mov_b32_e32 v84, v6
	v_mov_b32_e32 v88, v70
	v_mov_b32_e32 v85, v7
	v_mov_b32_e32 v89, v71
	v_mov_b32_e32 v86, v8
	v_mov_b32_e32 v90, v72
	v_mov_b32_e32 v87, v9
	v_mov_b32_e32 v91, v73
	v_cvt_pk_bf16_f32 v6, v92, v93
	v_lshlrev_b32_e32 v12, 16, v6
	v_and_b32_e32 v13, 0xffff0000, v6
	v_sub_f32_e32 v92, v92, v12
	v_sub_f32_e32 v93, v93, v13
	v_cvt_pk_bf16_f32 v70, v92, v93
	v_cvt_pk_bf16_f32 v7, v94, v95
	v_lshlrev_b32_e32 v12, 16, v7
	v_and_b32_e32 v13, 0xffff0000, v7
	v_sub_f32_e32 v94, v94, v12
	v_sub_f32_e32 v95, v95, v13
	v_cvt_pk_bf16_f32 v71, v94, v95
	v_cvt_pk_bf16_f32 v8, v96, v97
	v_lshlrev_b32_e32 v12, 16, v8
	v_and_b32_e32 v13, 0xffff0000, v8
	v_sub_f32_e32 v96, v96, v12
	v_sub_f32_e32 v97, v97, v13
	v_cvt_pk_bf16_f32 v72, v96, v97
	v_cvt_pk_bf16_f32 v9, v98, v99
	v_lshlrev_b32_e32 v12, 16, v9
	v_and_b32_e32 v13, 0xffff0000, v9
	v_sub_f32_e32 v98, v98, v12
	v_sub_f32_e32 v99, v99, v13
	v_cvt_pk_bf16_f32 v73, v98, v99
	v_mov_b32_e32 v92, v6
	v_mov_b32_e32 v96, v70
	v_mov_b32_e32 v93, v7
	v_mov_b32_e32 v97, v71
	v_mov_b32_e32 v94, v8
	v_mov_b32_e32 v98, v72
	v_mov_b32_e32 v95, v9
	v_mov_b32_e32 v99, v73
	v_cvt_pk_bf16_f32 v6, v100, v101
	v_lshlrev_b32_e32 v12, 16, v6
	v_and_b32_e32 v13, 0xffff0000, v6
	v_sub_f32_e32 v100, v100, v12
	v_sub_f32_e32 v101, v101, v13
	v_cvt_pk_bf16_f32 v70, v100, v101
	v_cvt_pk_bf16_f32 v7, v102, v103
	v_lshlrev_b32_e32 v12, 16, v7
	v_and_b32_e32 v13, 0xffff0000, v7
	v_sub_f32_e32 v102, v102, v12
	v_sub_f32_e32 v103, v103, v13
	v_cvt_pk_bf16_f32 v71, v102, v103
	v_cvt_pk_bf16_f32 v8, v104, v105
	v_lshlrev_b32_e32 v12, 16, v8
	v_and_b32_e32 v13, 0xffff0000, v8
	v_sub_f32_e32 v104, v104, v12
	v_sub_f32_e32 v105, v105, v13
	v_cvt_pk_bf16_f32 v72, v104, v105
	v_cvt_pk_bf16_f32 v9, v106, v107
	v_lshlrev_b32_e32 v12, 16, v9
	v_and_b32_e32 v13, 0xffff0000, v9
	v_sub_f32_e32 v106, v106, v12
	v_sub_f32_e32 v107, v107, v13
	v_cvt_pk_bf16_f32 v73, v106, v107
	v_mov_b32_e32 v100, v6
	v_mov_b32_e32 v104, v70
	v_mov_b32_e32 v101, v7
	v_mov_b32_e32 v105, v71
	v_mov_b32_e32 v102, v8
	v_mov_b32_e32 v106, v72
	v_mov_b32_e32 v103, v9
	v_mov_b32_e32 v107, v73
	v_cvt_pk_bf16_f32 v6, v108, v109
	v_lshlrev_b32_e32 v12, 16, v6
	v_and_b32_e32 v13, 0xffff0000, v6
	v_sub_f32_e32 v108, v108, v12
	v_sub_f32_e32 v109, v109, v13
	v_cvt_pk_bf16_f32 v70, v108, v109
	v_cvt_pk_bf16_f32 v7, v110, v111
	v_lshlrev_b32_e32 v12, 16, v7
	v_and_b32_e32 v13, 0xffff0000, v7
	v_sub_f32_e32 v110, v110, v12
	v_sub_f32_e32 v111, v111, v13
	v_cvt_pk_bf16_f32 v71, v110, v111
	v_cvt_pk_bf16_f32 v8, v76, v77
	v_lshlrev_b32_e32 v12, 16, v8
	v_and_b32_e32 v13, 0xffff0000, v8
	v_sub_f32_e32 v76, v76, v12
	v_sub_f32_e32 v77, v77, v13
	v_cvt_pk_bf16_f32 v72, v76, v77
	v_cvt_pk_bf16_f32 v9, v78, v79
	v_lshlrev_b32_e32 v12, 16, v9
	v_and_b32_e32 v13, 0xffff0000, v9
	v_sub_f32_e32 v78, v78, v12
	v_sub_f32_e32 v79, v79, v13
	v_cvt_pk_bf16_f32 v73, v78, v79
	v_mov_b32_e32 v108, v6
	v_mov_b32_e32 v76, v70
	v_mov_b32_e32 v109, v7
	v_mov_b32_e32 v77, v71
	v_mov_b32_e32 v110, v8
	v_mov_b32_e32 v78, v72
	v_mov_b32_e32 v111, v9
	v_mov_b32_e32 v79, v73
	s_lshl_b32 s55, s95, 7
	s_waitcnt vmcnt(24)
	s_nop 1
	v_mfma_f32_32x32x16_bf16 v[14:29], v[84:87], v[112:115], 0
	v_mfma_f32_32x32x16_bf16 v[14:29], v[84:87], v[128:131], v[14:29]
	v_mfma_f32_32x32x16_bf16 v[14:29], v[88:91], v[112:115], v[14:29]
	v_mfma_f32_32x32x16_bf16 v[14:29], v[92:95], v[116:119], v[14:29]
	v_mfma_f32_32x32x16_bf16 v[14:29], v[92:95], v[132:135], v[14:29]
	v_mfma_f32_32x32x16_bf16 v[14:29], v[96:99], v[116:119], v[14:29]
	v_mfma_f32_32x32x16_bf16 v[14:29], v[100:103], v[120:123], v[14:29]
	v_mfma_f32_32x32x16_bf16 v[14:29], v[100:103], v[136:139], v[14:29]
	v_mfma_f32_32x32x16_bf16 v[14:29], v[104:107], v[120:123], v[14:29]
	v_mfma_f32_32x32x16_bf16 v[14:29], v[108:111], v[124:127], v[14:29]
	v_mfma_f32_32x32x16_bf16 v[14:29], v[108:111], v[140:143], v[14:29]
	v_mfma_f32_32x32x16_bf16 v[14:29], v[76:79], v[124:127], v[14:29]
	v_add_u32_e32 v70, s55, v3
	v_cvt_f32_i32_e32 v71, v70
	v_mul_f32_e32 v71, 0xb9b8b5c6, v71
	v_sub_u32_e32 v72, 0x1000, v70
	v_add_u32_e32 v12, 0x1000, v70
	v_cmp_eq_u32_e32 vcc, 0, v70
	s_and_b64 s[16:17], vcc, s[14:15]
	s_andn2_b64 s[18:19], vcc, s[14:15]
	v_cndmask_b32_e64 v12, v12, 0, vcc
	v_cndmask_b32_e64 v72, v72, v12, s[14:15]
	v_lshlrev_b32_e32 v72, 1, v72
	s_nop 15
	v_mul_f32_e32 v10, s6, v71
	v_exp_f32_e32 v10, v10
	v_mov_b32_e32 v11, v72
	v_add_f32_e32 v10, 0x3d4ccccd, v10
	v_mul_f32_e32 v10, v10, v14
	v_add_f32_e32 v12, v48, v10
	v_cndmask_b32_e64 v10, v10, v12, s[18:19]
	v_cndmask_b32_e64 v10, v10, 0, s[16:17]
	v_cvt_pk_bf16_f32 v10, v10, v10
	global_store_short v11, v10, s[84:85]
	v_mul_f32_e32 v73, s7, v71
	v_exp_f32_e32 v73, v73
	v_add_u32_e32 v74, 0x4000, v72
	v_add_f32_e32 v73, 0x3d4ccccd, v73
	v_mul_f32_e32 v73, v73, v15
	v_add_f32_e32 v12, v49, v73
	v_cndmask_b32_e64 v73, v73, v12, s[18:19]
	v_cndmask_b32_e64 v73, v73, 0, s[16:17]
	v_cvt_pk_bf16_f32 v73, v73, v73
	global_store_short v74, v73, s[84:85]
	v_mul_f32_e32 v10, s10, v71
	v_exp_f32_e32 v10, v10
	v_add_u32_e32 v11, 0x8000, v72
	v_add_f32_e32 v10, 0x3d4ccccd, v10
	v_mul_f32_e32 v10, v10, v16
	v_add_f32_e32 v12, v50, v10
	v_cndmask_b32_e64 v10, v10, v12, s[18:19]
	v_cndmask_b32_e64 v10, v10, 0, s[16:17]
	v_cvt_pk_bf16_f32 v10, v10, v10
	global_store_short v11, v10, s[84:85]
	v_mul_f32_e32 v73, s11, v71
	v_exp_f32_e32 v73, v73
	v_add_u32_e32 v74, 0xc000, v72
	v_add_f32_e32 v73, 0x3d4ccccd, v73
	v_mul_f32_e32 v73, v73, v17
	v_add_f32_e32 v12, v51, v73
	v_cndmask_b32_e64 v73, v73, v12, s[18:19]
	v_cndmask_b32_e64 v73, v73, 0, s[16:17]
	v_cvt_pk_bf16_f32 v73, v73, v73
	global_store_short v74, v73, s[84:85]
	v_mul_f32_e32 v10, s24, v71
	v_exp_f32_e32 v10, v10
	v_add_u32_e32 v11, 0x10000, v72
	v_add_f32_e32 v10, 0x3d4ccccd, v10
	v_mul_f32_e32 v10, v10, v18
	v_add_f32_e32 v12, v52, v10
	v_cndmask_b32_e64 v10, v10, v12, s[18:19]
	v_cndmask_b32_e64 v10, v10, 0, s[16:17]
	v_cvt_pk_bf16_f32 v10, v10, v10
	global_store_short v11, v10, s[84:85]
	v_mul_f32_e32 v73, s26, v71
	v_exp_f32_e32 v73, v73
	v_add_u32_e32 v74, 0x14000, v72
	v_add_f32_e32 v73, 0x3d4ccccd, v73
	v_mul_f32_e32 v73, v73, v19
	v_add_f32_e32 v12, v53, v73
	v_cndmask_b32_e64 v73, v73, v12, s[18:19]
	v_cndmask_b32_e64 v73, v73, 0, s[16:17]
	v_cvt_pk_bf16_f32 v73, v73, v73
	global_store_short v74, v73, s[84:85]
	v_mul_f32_e32 v10, s32, v71
	v_exp_f32_e32 v10, v10
	v_add_u32_e32 v11, 0x18000, v72
	v_add_f32_e32 v10, 0x3d4ccccd, v10
	v_mul_f32_e32 v10, v10, v20
	v_add_f32_e32 v12, v54, v10
	v_cndmask_b32_e64 v10, v10, v12, s[18:19]
	v_cndmask_b32_e64 v10, v10, 0, s[16:17]
	v_cvt_pk_bf16_f32 v10, v10, v10
	global_store_short v11, v10, s[84:85]
	v_mul_f32_e32 v73, s35, v71
	v_exp_f32_e32 v73, v73
	v_add_u32_e32 v74, 0x1c000, v72
	v_add_f32_e32 v73, 0x3d4ccccd, v73
	v_mul_f32_e32 v73, v73, v21
	v_add_f32_e32 v12, v55, v73
	v_cndmask_b32_e64 v73, v73, v12, s[18:19]
	v_cndmask_b32_e64 v73, v73, 0, s[16:17]
	v_cvt_pk_bf16_f32 v73, v73, v73
	global_store_short v74, v73, s[84:85]
	v_mul_f32_e32 v10, s41, v71
	v_exp_f32_e32 v10, v10
	v_add_u32_e32 v11, 0x20000, v72
	v_add_f32_e32 v10, 0x3d4ccccd, v10
	v_mul_f32_e32 v10, v10, v22
	v_add_f32_e32 v12, v56, v10
	v_cndmask_b32_e64 v10, v10, v12, s[18:19]
	v_cndmask_b32_e64 v10, v10, 0, s[16:17]
	v_cvt_pk_bf16_f32 v10, v10, v10
	global_store_short v11, v10, s[84:85]
	v_mul_f32_e32 v73, s44, v71
	v_exp_f32_e32 v73, v73
	v_add_u32_e32 v74, 0x24000, v72
	v_add_f32_e32 v73, 0x3d4ccccd, v73
	v_mul_f32_e32 v73, v73, v23
	v_add_f32_e32 v12, v57, v73
	v_cndmask_b32_e64 v73, v73, v12, s[18:19]
	v_cndmask_b32_e64 v73, v73, 0, s[16:17]
	v_cvt_pk_bf16_f32 v73, v73, v73
	global_store_short v74, v73, s[84:85]
	v_mul_f32_e32 v10, s45, v71
	v_exp_f32_e32 v10, v10
	v_add_u32_e32 v11, 0x28000, v72
	v_add_f32_e32 v10, 0x3d4ccccd, v10
	v_mul_f32_e32 v10, v10, v24
	v_add_f32_e32 v12, v58, v10
	v_cndmask_b32_e64 v10, v10, v12, s[18:19]
	v_cndmask_b32_e64 v10, v10, 0, s[16:17]
	v_cvt_pk_bf16_f32 v10, v10, v10
	global_store_short v11, v10, s[84:85]
	v_mul_f32_e32 v73, s47, v71
	v_exp_f32_e32 v73, v73
	v_add_u32_e32 v74, 0x2c000, v72
	v_add_f32_e32 v73, 0x3d4ccccd, v73
	v_mul_f32_e32 v73, v73, v25
	v_add_f32_e32 v12, v59, v73
	v_cndmask_b32_e64 v73, v73, v12, s[18:19]
	v_cndmask_b32_e64 v73, v73, 0, s[16:17]
	v_cvt_pk_bf16_f32 v73, v73, v73
	global_store_short v74, v73, s[84:85]
	v_mul_f32_e32 v10, s48, v71
	v_exp_f32_e32 v10, v10
	v_add_u32_e32 v11, 0x30000, v72
	v_add_f32_e32 v10, 0x3d4ccccd, v10
	v_mul_f32_e32 v10, v10, v26
	v_add_f32_e32 v12, v66, v10
	v_cndmask_b32_e64 v10, v10, v12, s[18:19]
	v_cndmask_b32_e64 v10, v10, 0, s[16:17]
	v_cvt_pk_bf16_f32 v10, v10, v10
	global_store_short v11, v10, s[84:85]
	v_mul_f32_e32 v73, s49, v71
	v_exp_f32_e32 v73, v73
	v_add_u32_e32 v74, 0x34000, v72
	v_add_f32_e32 v73, 0x3d4ccccd, v73
	v_mul_f32_e32 v73, v73, v27
	v_add_f32_e32 v12, v67, v73
	v_cndmask_b32_e64 v73, v73, v12, s[18:19]
	v_cndmask_b32_e64 v73, v73, 0, s[16:17]
	v_cvt_pk_bf16_f32 v73, v73, v73
	global_store_short v74, v73, s[84:85]
	v_mul_f32_e32 v10, s52, v71
	v_exp_f32_e32 v10, v10
	v_add_u32_e32 v11, 0x38000, v72
	v_add_f32_e32 v10, 0x3d4ccccd, v10
	v_mul_f32_e32 v10, v10, v28
	v_add_f32_e32 v12, v68, v10
	v_cndmask_b32_e64 v10, v10, v12, s[18:19]
	v_cndmask_b32_e64 v10, v10, 0, s[16:17]
	v_cvt_pk_bf16_f32 v10, v10, v10
	global_store_short v11, v10, s[84:85]
	v_mul_f32_e32 v73, s53, v71
	v_exp_f32_e32 v73, v73
	v_add_u32_e32 v74, 0x3c000, v72
	v_add_f32_e32 v73, 0x3d4ccccd, v73
	v_mul_f32_e32 v73, v73, v29
	v_add_f32_e32 v12, v69, v73
	v_cndmask_b32_e64 v73, v73, v12, s[18:19]
	v_cndmask_b32_e64 v73, v73, 0, s[16:17]
	v_cvt_pk_bf16_f32 v73, v73, v73
	global_store_short v74, v73, s[84:85]
	s_add_i32 s55, s55, 32
	s_waitcnt vmcnt(32)
	s_nop 1
	v_mfma_f32_32x32x16_bf16 v[14:29], v[84:87], v[144:147], 0
	v_mfma_f32_32x32x16_bf16 v[14:29], v[84:87], v[160:163], v[14:29]
	v_mfma_f32_32x32x16_bf16 v[14:29], v[88:91], v[144:147], v[14:29]
	v_mfma_f32_32x32x16_bf16 v[14:29], v[92:95], v[148:151], v[14:29]
	v_mfma_f32_32x32x16_bf16 v[14:29], v[92:95], v[164:167], v[14:29]
	v_mfma_f32_32x32x16_bf16 v[14:29], v[96:99], v[148:151], v[14:29]
	v_mfma_f32_32x32x16_bf16 v[14:29], v[100:103], v[152:155], v[14:29]
	v_mfma_f32_32x32x16_bf16 v[14:29], v[100:103], v[168:171], v[14:29]
	v_mfma_f32_32x32x16_bf16 v[14:29], v[104:107], v[152:155], v[14:29]
	v_mfma_f32_32x32x16_bf16 v[14:29], v[108:111], v[156:159], v[14:29]
	v_mfma_f32_32x32x16_bf16 v[14:29], v[108:111], v[172:175], v[14:29]
	v_mfma_f32_32x32x16_bf16 v[14:29], v[76:79], v[156:159], v[14:29]
	v_add_u32_e32 v70, s55, v3
	v_cvt_f32_i32_e32 v71, v70
	v_mul_f32_e32 v71, 0xb9b8b5c6, v71
	v_sub_u32_e32 v72, 0x1000, v70
	v_add_u32_e32 v12, 0x1000, v70
	v_cndmask_b32_e64 v72, v72, v12, s[14:15]
	v_lshlrev_b32_e32 v72, 1, v72
	s_nop 15
	v_mul_f32_e32 v10, s6, v71
	v_exp_f32_e32 v10, v10
	v_mov_b32_e32 v11, v72
	v_add_f32_e32 v10, 0x3d4ccccd, v10
	v_mul_f32_e32 v10, v10, v14
	v_cvt_pk_bf16_f32 v10, v10, v10
	global_store_short v11, v10, s[84:85]
	v_mul_f32_e32 v73, s7, v71
	v_exp_f32_e32 v73, v73
	v_add_u32_e32 v74, 0x4000, v72
	v_add_f32_e32 v73, 0x3d4ccccd, v73
	v_mul_f32_e32 v73, v73, v15
	v_cvt_pk_bf16_f32 v73, v73, v73
	global_store_short v74, v73, s[84:85]
	v_mul_f32_e32 v10, s10, v71
	v_exp_f32_e32 v10, v10
	v_add_u32_e32 v11, 0x8000, v72
	v_add_f32_e32 v10, 0x3d4ccccd, v10
	v_mul_f32_e32 v10, v10, v16
	v_cvt_pk_bf16_f32 v10, v10, v10
	global_store_short v11, v10, s[84:85]
	v_mul_f32_e32 v73, s11, v71
	v_exp_f32_e32 v73, v73
	v_add_u32_e32 v74, 0xc000, v72
	v_add_f32_e32 v73, 0x3d4ccccd, v73
	v_mul_f32_e32 v73, v73, v17
	v_cvt_pk_bf16_f32 v73, v73, v73
	global_store_short v74, v73, s[84:85]
	v_mul_f32_e32 v10, s24, v71
	v_exp_f32_e32 v10, v10
	v_add_u32_e32 v11, 0x10000, v72
	v_add_f32_e32 v10, 0x3d4ccccd, v10
	v_mul_f32_e32 v10, v10, v18
	v_cvt_pk_bf16_f32 v10, v10, v10
	global_store_short v11, v10, s[84:85]
	v_mul_f32_e32 v73, s26, v71
	v_exp_f32_e32 v73, v73
	v_add_u32_e32 v74, 0x14000, v72
	v_add_f32_e32 v73, 0x3d4ccccd, v73
	v_mul_f32_e32 v73, v73, v19
	v_cvt_pk_bf16_f32 v73, v73, v73
	global_store_short v74, v73, s[84:85]
	v_mul_f32_e32 v10, s32, v71
	v_exp_f32_e32 v10, v10
	v_add_u32_e32 v11, 0x18000, v72
	v_add_f32_e32 v10, 0x3d4ccccd, v10
	v_mul_f32_e32 v10, v10, v20
	v_cvt_pk_bf16_f32 v10, v10, v10
	global_store_short v11, v10, s[84:85]
	v_mul_f32_e32 v73, s35, v71
	v_exp_f32_e32 v73, v73
	v_add_u32_e32 v74, 0x1c000, v72
	v_add_f32_e32 v73, 0x3d4ccccd, v73
	v_mul_f32_e32 v73, v73, v21
	v_cvt_pk_bf16_f32 v73, v73, v73
	global_store_short v74, v73, s[84:85]
	v_mul_f32_e32 v10, s41, v71
	v_exp_f32_e32 v10, v10
	v_add_u32_e32 v11, 0x20000, v72
	v_add_f32_e32 v10, 0x3d4ccccd, v10
	v_mul_f32_e32 v10, v10, v22
	v_cvt_pk_bf16_f32 v10, v10, v10
	global_store_short v11, v10, s[84:85]
	v_mul_f32_e32 v73, s44, v71
	v_exp_f32_e32 v73, v73
	v_add_u32_e32 v74, 0x24000, v72
	v_add_f32_e32 v73, 0x3d4ccccd, v73
	v_mul_f32_e32 v73, v73, v23
	v_cvt_pk_bf16_f32 v73, v73, v73
	global_store_short v74, v73, s[84:85]
	v_mul_f32_e32 v10, s45, v71
	v_exp_f32_e32 v10, v10
	v_add_u32_e32 v11, 0x28000, v72
	v_add_f32_e32 v10, 0x3d4ccccd, v10
	v_mul_f32_e32 v10, v10, v24
	v_cvt_pk_bf16_f32 v10, v10, v10
	global_store_short v11, v10, s[84:85]
	v_mul_f32_e32 v73, s47, v71
	v_exp_f32_e32 v73, v73
	v_add_u32_e32 v74, 0x2c000, v72
	v_add_f32_e32 v73, 0x3d4ccccd, v73
	v_mul_f32_e32 v73, v73, v25
	v_cvt_pk_bf16_f32 v73, v73, v73
	global_store_short v74, v73, s[84:85]
	v_mul_f32_e32 v10, s48, v71
	v_exp_f32_e32 v10, v10
	v_add_u32_e32 v11, 0x30000, v72
	v_add_f32_e32 v10, 0x3d4ccccd, v10
	v_mul_f32_e32 v10, v10, v26
	v_cvt_pk_bf16_f32 v10, v10, v10
	global_store_short v11, v10, s[84:85]
	v_mul_f32_e32 v73, s49, v71
	v_exp_f32_e32 v73, v73
	v_add_u32_e32 v74, 0x34000, v72
	v_add_f32_e32 v73, 0x3d4ccccd, v73
	v_mul_f32_e32 v73, v73, v27
	v_cvt_pk_bf16_f32 v73, v73, v73
	global_store_short v74, v73, s[84:85]
	v_mul_f32_e32 v10, s52, v71
	v_exp_f32_e32 v10, v10
	v_add_u32_e32 v11, 0x38000, v72
	v_add_f32_e32 v10, 0x3d4ccccd, v10
	v_mul_f32_e32 v10, v10, v28
	v_cvt_pk_bf16_f32 v10, v10, v10
	global_store_short v11, v10, s[84:85]
	v_mul_f32_e32 v73, s53, v71
	v_exp_f32_e32 v73, v73
	v_add_u32_e32 v74, 0x3c000, v72
	v_add_f32_e32 v73, 0x3d4ccccd, v73
	v_mul_f32_e32 v73, v73, v29
	v_cvt_pk_bf16_f32 v73, v73, v73
	global_store_short v74, v73, s[84:85]
	s_add_i32 s55, s55, 32
	s_waitcnt vmcnt(40)
	s_nop 1
	v_mfma_f32_32x32x16_bf16 v[14:29], v[84:87], v[176:179], 0
	v_mfma_f32_32x32x16_bf16 v[14:29], v[84:87], v[192:195], v[14:29]
	v_mfma_f32_32x32x16_bf16 v[14:29], v[88:91], v[176:179], v[14:29]
	v_mfma_f32_32x32x16_bf16 v[14:29], v[92:95], v[180:183], v[14:29]
	v_mfma_f32_32x32x16_bf16 v[14:29], v[92:95], v[196:199], v[14:29]
	v_mfma_f32_32x32x16_bf16 v[14:29], v[96:99], v[180:183], v[14:29]
	v_mfma_f32_32x32x16_bf16 v[14:29], v[100:103], v[184:187], v[14:29]
	v_mfma_f32_32x32x16_bf16 v[14:29], v[100:103], v[200:203], v[14:29]
	v_mfma_f32_32x32x16_bf16 v[14:29], v[104:107], v[184:187], v[14:29]
	v_mfma_f32_32x32x16_bf16 v[14:29], v[108:111], v[188:191], v[14:29]
	v_mfma_f32_32x32x16_bf16 v[14:29], v[108:111], v[204:207], v[14:29]
	v_mfma_f32_32x32x16_bf16 v[14:29], v[76:79], v[188:191], v[14:29]
	v_add_u32_e32 v70, s55, v3
	v_cvt_f32_i32_e32 v71, v70
	v_mul_f32_e32 v71, 0xb9b8b5c6, v71
	v_sub_u32_e32 v72, 0x1000, v70
	v_add_u32_e32 v12, 0x1000, v70
	v_cndmask_b32_e64 v72, v72, v12, s[14:15]
	v_lshlrev_b32_e32 v72, 1, v72
	s_nop 15
	v_mul_f32_e32 v10, s6, v71
	v_exp_f32_e32 v10, v10
	v_mov_b32_e32 v11, v72
	v_add_f32_e32 v10, 0x3d4ccccd, v10
	v_mul_f32_e32 v10, v10, v14
	v_cvt_pk_bf16_f32 v10, v10, v10
	global_store_short v11, v10, s[84:85]
	v_mul_f32_e32 v73, s7, v71
	v_exp_f32_e32 v73, v73
	v_add_u32_e32 v74, 0x4000, v72
	v_add_f32_e32 v73, 0x3d4ccccd, v73
	v_mul_f32_e32 v73, v73, v15
	v_cvt_pk_bf16_f32 v73, v73, v73
	global_store_short v74, v73, s[84:85]
	v_mul_f32_e32 v10, s10, v71
	v_exp_f32_e32 v10, v10
	v_add_u32_e32 v11, 0x8000, v72
	v_add_f32_e32 v10, 0x3d4ccccd, v10
	v_mul_f32_e32 v10, v10, v16
	v_cvt_pk_bf16_f32 v10, v10, v10
	global_store_short v11, v10, s[84:85]
	v_mul_f32_e32 v73, s11, v71
	v_exp_f32_e32 v73, v73
	v_add_u32_e32 v74, 0xc000, v72
	v_add_f32_e32 v73, 0x3d4ccccd, v73
	v_mul_f32_e32 v73, v73, v17
	v_cvt_pk_bf16_f32 v73, v73, v73
	global_store_short v74, v73, s[84:85]
	v_mul_f32_e32 v10, s24, v71
	v_exp_f32_e32 v10, v10
	v_add_u32_e32 v11, 0x10000, v72
	v_add_f32_e32 v10, 0x3d4ccccd, v10
	v_mul_f32_e32 v10, v10, v18
	v_cvt_pk_bf16_f32 v10, v10, v10
	global_store_short v11, v10, s[84:85]
	v_mul_f32_e32 v73, s26, v71
	v_exp_f32_e32 v73, v73
	v_add_u32_e32 v74, 0x14000, v72
	v_add_f32_e32 v73, 0x3d4ccccd, v73
	v_mul_f32_e32 v73, v73, v19
	v_cvt_pk_bf16_f32 v73, v73, v73
	global_store_short v74, v73, s[84:85]
	v_mul_f32_e32 v10, s32, v71
	v_exp_f32_e32 v10, v10
	v_add_u32_e32 v11, 0x18000, v72
	v_add_f32_e32 v10, 0x3d4ccccd, v10
	v_mul_f32_e32 v10, v10, v20
	v_cvt_pk_bf16_f32 v10, v10, v10
	global_store_short v11, v10, s[84:85]
	v_mul_f32_e32 v73, s35, v71
	v_exp_f32_e32 v73, v73
	v_add_u32_e32 v74, 0x1c000, v72
	v_add_f32_e32 v73, 0x3d4ccccd, v73
	v_mul_f32_e32 v73, v73, v21
	v_cvt_pk_bf16_f32 v73, v73, v73
	global_store_short v74, v73, s[84:85]
	v_mul_f32_e32 v10, s41, v71
	v_exp_f32_e32 v10, v10
	v_add_u32_e32 v11, 0x20000, v72
	v_add_f32_e32 v10, 0x3d4ccccd, v10
	v_mul_f32_e32 v10, v10, v22
	v_cvt_pk_bf16_f32 v10, v10, v10
	global_store_short v11, v10, s[84:85]
	v_mul_f32_e32 v73, s44, v71
	v_exp_f32_e32 v73, v73
	v_add_u32_e32 v74, 0x24000, v72
	v_add_f32_e32 v73, 0x3d4ccccd, v73
	v_mul_f32_e32 v73, v73, v23
	v_cvt_pk_bf16_f32 v73, v73, v73
	global_store_short v74, v73, s[84:85]
	v_mul_f32_e32 v10, s45, v71
	v_exp_f32_e32 v10, v10
	v_add_u32_e32 v11, 0x28000, v72
	v_add_f32_e32 v10, 0x3d4ccccd, v10
	v_mul_f32_e32 v10, v10, v24
	v_cvt_pk_bf16_f32 v10, v10, v10
	global_store_short v11, v10, s[84:85]
	v_mul_f32_e32 v73, s47, v71
	v_exp_f32_e32 v73, v73
	v_add_u32_e32 v74, 0x2c000, v72
	v_add_f32_e32 v73, 0x3d4ccccd, v73
	v_mul_f32_e32 v73, v73, v25
	v_cvt_pk_bf16_f32 v73, v73, v73
	global_store_short v74, v73, s[84:85]
	v_mul_f32_e32 v10, s48, v71
	v_exp_f32_e32 v10, v10
	v_add_u32_e32 v11, 0x30000, v72
	v_add_f32_e32 v10, 0x3d4ccccd, v10
	v_mul_f32_e32 v10, v10, v26
	v_cvt_pk_bf16_f32 v10, v10, v10
	global_store_short v11, v10, s[84:85]
	v_mul_f32_e32 v73, s49, v71
	v_exp_f32_e32 v73, v73
	v_add_u32_e32 v74, 0x34000, v72
	v_add_f32_e32 v73, 0x3d4ccccd, v73
	v_mul_f32_e32 v73, v73, v27
	v_cvt_pk_bf16_f32 v73, v73, v73
	global_store_short v74, v73, s[84:85]
	v_mul_f32_e32 v10, s52, v71
	v_exp_f32_e32 v10, v10
	v_add_u32_e32 v11, 0x38000, v72
	v_add_f32_e32 v10, 0x3d4ccccd, v10
	v_mul_f32_e32 v10, v10, v28
	v_cvt_pk_bf16_f32 v10, v10, v10
	global_store_short v11, v10, s[84:85]
	v_mul_f32_e32 v73, s53, v71
	v_exp_f32_e32 v73, v73
	v_add_u32_e32 v74, 0x3c000, v72
	v_add_f32_e32 v73, 0x3d4ccccd, v73
	v_mul_f32_e32 v73, v73, v29
	v_cvt_pk_bf16_f32 v73, v73, v73
	global_store_short v74, v73, s[84:85]
	s_add_i32 s55, s55, 32
	s_waitcnt vmcnt(48)
	s_nop 1
	v_mfma_f32_32x32x16_bf16 v[14:29], v[84:87], v[208:211], 0
	v_mfma_f32_32x32x16_bf16 v[14:29], v[84:87], v[224:227], v[14:29]
	v_mfma_f32_32x32x16_bf16 v[14:29], v[88:91], v[208:211], v[14:29]
	v_mfma_f32_32x32x16_bf16 v[14:29], v[92:95], v[212:215], v[14:29]
	v_mfma_f32_32x32x16_bf16 v[14:29], v[92:95], v[228:231], v[14:29]
	v_mfma_f32_32x32x16_bf16 v[14:29], v[96:99], v[212:215], v[14:29]
	v_mfma_f32_32x32x16_bf16 v[14:29], v[100:103], v[216:219], v[14:29]
	v_mfma_f32_32x32x16_bf16 v[14:29], v[100:103], v[232:235], v[14:29]
	v_mfma_f32_32x32x16_bf16 v[14:29], v[104:107], v[216:219], v[14:29]
	v_mfma_f32_32x32x16_bf16 v[14:29], v[108:111], v[220:223], v[14:29]
	v_mfma_f32_32x32x16_bf16 v[14:29], v[108:111], v[236:239], v[14:29]
	v_mfma_f32_32x32x16_bf16 v[14:29], v[76:79], v[220:223], v[14:29]
	v_add_u32_e32 v70, s55, v3
	v_cvt_f32_i32_e32 v71, v70
	v_mul_f32_e32 v71, 0xb9b8b5c6, v71
	v_sub_u32_e32 v72, 0x1000, v70
	v_add_u32_e32 v12, 0x1000, v70
	v_cndmask_b32_e64 v72, v72, v12, s[14:15]
	v_lshlrev_b32_e32 v72, 1, v72
	s_nop 15
	v_mul_f32_e32 v10, s6, v71
	v_exp_f32_e32 v10, v10
	v_mov_b32_e32 v11, v72
	v_add_f32_e32 v10, 0x3d4ccccd, v10
	v_mul_f32_e32 v10, v10, v14
	v_cvt_pk_bf16_f32 v10, v10, v10
	global_store_short v11, v10, s[84:85]
	v_mul_f32_e32 v73, s7, v71
	v_exp_f32_e32 v73, v73
	v_add_u32_e32 v74, 0x4000, v72
	v_add_f32_e32 v73, 0x3d4ccccd, v73
	v_mul_f32_e32 v73, v73, v15
	v_cvt_pk_bf16_f32 v73, v73, v73
	global_store_short v74, v73, s[84:85]
	v_mul_f32_e32 v10, s10, v71
	v_exp_f32_e32 v10, v10
	v_add_u32_e32 v11, 0x8000, v72
	v_add_f32_e32 v10, 0x3d4ccccd, v10
	v_mul_f32_e32 v10, v10, v16
	v_cvt_pk_bf16_f32 v10, v10, v10
	global_store_short v11, v10, s[84:85]
	v_mul_f32_e32 v73, s11, v71
	v_exp_f32_e32 v73, v73
	v_add_u32_e32 v74, 0xc000, v72
	v_add_f32_e32 v73, 0x3d4ccccd, v73
	v_mul_f32_e32 v73, v73, v17
	v_cvt_pk_bf16_f32 v73, v73, v73
	global_store_short v74, v73, s[84:85]
	v_mul_f32_e32 v10, s24, v71
	v_exp_f32_e32 v10, v10
	v_add_u32_e32 v11, 0x10000, v72
	v_add_f32_e32 v10, 0x3d4ccccd, v10
	v_mul_f32_e32 v10, v10, v18
	v_cvt_pk_bf16_f32 v10, v10, v10
	global_store_short v11, v10, s[84:85]
	v_mul_f32_e32 v73, s26, v71
	v_exp_f32_e32 v73, v73
	v_add_u32_e32 v74, 0x14000, v72
	v_add_f32_e32 v73, 0x3d4ccccd, v73
	v_mul_f32_e32 v73, v73, v19
	v_cvt_pk_bf16_f32 v73, v73, v73
	global_store_short v74, v73, s[84:85]
	v_mul_f32_e32 v10, s32, v71
	v_exp_f32_e32 v10, v10
	v_add_u32_e32 v11, 0x18000, v72
	v_add_f32_e32 v10, 0x3d4ccccd, v10
	v_mul_f32_e32 v10, v10, v20
	v_cvt_pk_bf16_f32 v10, v10, v10
	global_store_short v11, v10, s[84:85]
	v_mul_f32_e32 v73, s35, v71
	v_exp_f32_e32 v73, v73
	v_add_u32_e32 v74, 0x1c000, v72
	v_add_f32_e32 v73, 0x3d4ccccd, v73
	v_mul_f32_e32 v73, v73, v21
	v_cvt_pk_bf16_f32 v73, v73, v73
	global_store_short v74, v73, s[84:85]
	v_mul_f32_e32 v10, s41, v71
	v_exp_f32_e32 v10, v10
	v_add_u32_e32 v11, 0x20000, v72
	v_add_f32_e32 v10, 0x3d4ccccd, v10
	v_mul_f32_e32 v10, v10, v22
	v_cvt_pk_bf16_f32 v10, v10, v10
	global_store_short v11, v10, s[84:85]
	v_mul_f32_e32 v73, s44, v71
	v_exp_f32_e32 v73, v73
	v_add_u32_e32 v74, 0x24000, v72
	v_add_f32_e32 v73, 0x3d4ccccd, v73
	v_mul_f32_e32 v73, v73, v23
	v_cvt_pk_bf16_f32 v73, v73, v73
	global_store_short v74, v73, s[84:85]
	v_mul_f32_e32 v10, s45, v71
	v_exp_f32_e32 v10, v10
	v_add_u32_e32 v11, 0x28000, v72
	v_add_f32_e32 v10, 0x3d4ccccd, v10
	v_mul_f32_e32 v10, v10, v24
	v_cvt_pk_bf16_f32 v10, v10, v10
	global_store_short v11, v10, s[84:85]
	v_mul_f32_e32 v73, s47, v71
	v_exp_f32_e32 v73, v73
	v_add_u32_e32 v74, 0x2c000, v72
	v_add_f32_e32 v73, 0x3d4ccccd, v73
	v_mul_f32_e32 v73, v73, v25
	v_cvt_pk_bf16_f32 v73, v73, v73
	global_store_short v74, v73, s[84:85]
	v_mul_f32_e32 v10, s48, v71
	v_exp_f32_e32 v10, v10
	v_add_u32_e32 v11, 0x30000, v72
	v_add_f32_e32 v10, 0x3d4ccccd, v10
	v_mul_f32_e32 v10, v10, v26
	v_cvt_pk_bf16_f32 v10, v10, v10
	global_store_short v11, v10, s[84:85]
	v_mul_f32_e32 v73, s49, v71
	v_exp_f32_e32 v73, v73
	v_add_u32_e32 v74, 0x34000, v72
	v_add_f32_e32 v73, 0x3d4ccccd, v73
	v_mul_f32_e32 v73, v73, v27
	v_cvt_pk_bf16_f32 v73, v73, v73
	global_store_short v74, v73, s[84:85]
	v_mul_f32_e32 v10, s52, v71
	v_exp_f32_e32 v10, v10
	v_add_u32_e32 v11, 0x38000, v72
	v_add_f32_e32 v10, 0x3d4ccccd, v10
	v_mul_f32_e32 v10, v10, v28
	v_cvt_pk_bf16_f32 v10, v10, v10
	global_store_short v11, v10, s[84:85]
	v_mul_f32_e32 v73, s53, v71
	v_exp_f32_e32 v73, v73
	v_add_u32_e32 v74, 0x3c000, v72
	v_add_f32_e32 v73, 0x3d4ccccd, v73
	v_mul_f32_e32 v73, v73, v29
	v_cvt_pk_bf16_f32 v73, v73, v73
	global_store_short v74, v73, s[84:85]
	s_add_i32 s93, s93, s70
	s_branch .Lpf_item
.Lpf_end:
.LBB0_225:
	s_cmp_gt_i32 s69, 3
	s_cselect_b64 s[6:7], -1, 0
	s_and_b64 s[8:9], s[8:9], s[6:7]
	s_andn2_b64 vcc, exec, s[8:9]
	s_cbranch_vccnz .LBB0_293
	s_cmpk_lt_u32 s69, 0x3e9
	s_mov_b64 s[8:9], -1
	s_cbranch_scc0 .LBB0_280
	s_waitcnt vmcnt(0)
	s_waitcnt vmcnt(0)
	s_barrier
	s_mov_b64 s[8:9], exec
	v_readlane_b32 s10, v240, 4
	v_readlane_b32 s11, v240, 5
	s_and_b64 s[10:11], s[8:9], s[10:11]
	s_mov_b64 exec, s[10:11]
	s_cbranch_execz .LBB0_279
	s_add_i32 s10, 0, 0x26000
	v_mov_b32_e32 v2, s10
	s_waitcnt vmcnt(0) expcnt(0) lgkmcnt(0)
	ds_read_b32 v4, v2
	s_add_i32 s10, 0, 0x26004
	v_mov_b32_e32 v2, s10
	ds_read_b32 v2, v2
	s_waitcnt lgkmcnt(1)
	v_cmp_ne_u32_e32 vcc, 0, v4
	s_cbranch_vccnz .LBB0_243
	s_load_dword s10, s[0:1], 0x110
	s_mov_b32 s44, 1
	v_mov_b32_e32 v18, 0
	s_waitcnt lgkmcnt(0)
	s_mul_i32 s33, s71, s10
	s_add_u32 s10, s66, 0x1bc0200
	s_addc_u32 s11, s67, 0
	s_add_u32 s12, s66, 0x1bc0400
	s_addc_u32 s13, s67, 0
	s_add_u32 s14, s66, 0x1bc0500
	s_addc_u32 s15, s67, 0
	s_add_u32 s16, s66, 0x1bc0600
	s_addc_u32 s17, s67, 0
	s_add_u32 s18, s66, 0x1bc0700
	s_addc_u32 s19, s67, 0
	s_add_u32 s20, s66, 0x1bc0800
	s_addc_u32 s21, s67, 0
	s_add_u32 s22, s66, 0x1bc0900
	s_addc_u32 s23, s67, 0
	s_add_u32 s24, s66, 0x1bc0a00
	s_addc_u32 s25, s67, 0
	s_add_u32 s26, s66, 0x1bc0b00
	s_addc_u32 s27, s67, 0
	s_add_u32 s28, s66, 0x1bc0c00
	s_addc_u32 s29, s67, 0
	s_add_u32 s30, s66, 0x1bc0d00
	s_addc_u32 s31, s67, 0
	s_add_u32 s34, s66, 0x1bc0e00
	s_addc_u32 s35, s67, 0
	s_add_u32 s36, s66, 0x1bc0f00
	s_addc_u32 s37, s67, 0
	s_add_u32 s38, s66, 0x1bc1000
	s_addc_u32 s39, s67, 0
	s_add_u32 s40, s66, 0x1bc1100
	s_addc_u32 s41, s67, 0
	s_add_u32 s42, s66, 0x1bc1200
	s_addc_u32 s43, s67, 0
	s_add_u32 s48, s66, 0x1bc1300
	s_mul_i32 s33, s33, s70
	s_addc_u32 s49, s67, 0
	s_branch .LBB0_231

.LBB0_297:
	s_lshl_b32 s10, s78, 2
	s_and_b32 s79, s10, 0x3fc
	s_cmpk_gt_u32 s78, 0xff
	s_cbranch_scc1 .Lpf_skipw
	v_mov_b32_e32 v2, 0
	s_and_saveexec_b64 s[10:11], s[6:7]
	s_cbranch_execz .LBB0_299
	v_or_b32_e32 v2, s79, v121
	v_lshlrev_b32_e32 v2, 2, v2
	global_load_dword v2, v2, s[86:87]

.Lpf_skipw:
	s_cmpk_lt_u32 s78, 0x100
	s_cselect_b64 s[30:31], -1, 0
	s_cmpk_gt_u32 s78, 0xff
	s_cselect_b64 s[42:43], -1, 0
	s_lshl_b32 s84, s79, 2
	v_mov_b32_e32 v18, s84
	global_load_dwordx4 v[18:21], v18, s[88:89]
	s_and_saveexec_b64 s[10:11], s[4:5]
	s_and_b64 s[12:13], s[30:31], exec
	s_cselect_b32 s12, 10, 14
	v_lshlrev_b32_e32 v38, s12, v1
	v_add_u32_e32 v38, 0, v38
	ds_write_b16 v38, v109
	s_or_b64 exec, exec, s[10:11]
	s_and_b64 s[10:11], s[30:31], exec
	s_cselect_b32 s46, s1, 0x1000
	s_lshl_b32 s36, s46, 4
	s_add_i32 s47, s36, 0
	s_or_b32 s81, s79, 1
	s_or_b32 s33, s79, 2
	s_or_b32 s80, s79, 3
	s_lshr_b32 s92, s46, 5
	v_readfirstlane_b32 s12, v153
	s_cmp_ge_i32 s12, s92
	s_cbranch_scc1 .LBB0_390
	s_and_b64 vcc, exec, s[42:43]
	s_cbranch_vccnz .Lpf_copy
	s_waitcnt vmcnt(0)
	v_cvt_pk_bf16_f32 v38, v28, s0
	v_lshlrev_b32_e32 v38, 16, v38
	v_sub_f32_e32 v39, v28, v38
	v_cvt_pk_bf16_f32 v28, v27, s0
	v_lshlrev_b32_e32 v28, 16, v28
	v_sub_f32_e32 v40, v27, v28
	v_cvt_pk_bf16_f32 v27, v26, s0
	v_lshlrev_b32_e32 v27, 16, v27
	v_sub_f32_e32 v41, v26, v27
	v_cvt_pk_bf16_f32 v26, v25, s0
	v_lshlrev_b32_e32 v26, 16, v26
	v_sub_f32_e32 v42, v25, v26
	v_cvt_pk_bf16_f32 v25, v24, s0
	v_lshlrev_b32_e32 v25, 16, v25
	v_sub_f32_e32 v43, v24, v25
	v_cvt_pk_bf16_f32 v24, v23, s0
	v_lshlrev_b32_e32 v24, 16, v24
	v_sub_f32_e32 v44, v23, v24
	v_cvt_pk_bf16_f32 v23, v22, s0
	v_lshlrev_b32_e32 v23, 16, v23
	v_sub_f32_e32 v45, v22, v23
	v_cvt_pk_bf16_f32 v22, v29, s0
	v_lshlrev_b32_e32 v46, 16, v22
	v_cvt_pk_bf16_f32 v22, v23, v24
	v_cvt_pk_bf16_f32 v23, v25, v26
	v_cvt_pk_bf16_f32 v25, v38, v46
	v_cvt_f32_u32_e32 v38, s79
	s_lshl_b32 s10, s12, 13
	s_add_i32 s37, s47, s10
	v_cvt_pk_bf16_f32 v24, v27, v28
	v_cvt_pk_bf16_f32 v28, v41, v40
	v_div_scale_f32 v40, s[10:11], s74, s74, v38
	v_rcp_f32_e32 v41, v40
	v_cvt_pk_bf16_f32 v27, v43, v42
	v_cvt_pk_bf16_f32 v26, v45, v44
	v_cvt_f32_u32_e32 v45, s81
	v_fma_f32 v42, -v40, v41, 1.0
	v_fmac_f32_e32 v41, v42, v41
	v_div_scale_f32 v42, vcc, v38, s74, v38
	v_mul_f32_e32 v43, v42, v41
	v_fma_f32 v44, -v40, v43, v42
	v_sub_f32_e32 v29, v29, v46
	s_add_i32 s10, s46, -1
	v_fmac_f32_e32 v43, v44, v41
	v_cvt_pk_bf16_f32 v29, v39, v29
	v_cvt_f32_u32_e32 v39, s10
	v_fma_f32 v40, -v40, v43, v42
	v_div_scale_f32 v42, s[10:11], s74, s74, v45
	v_rcp_f32_e32 v44, v42
	v_div_fmas_f32 v40, v40, v41, v43
	v_div_fixup_f32 v38, v40, s74, v38
	v_fmamk_f32 v88, v38, 0xc1447cbd, v168
	v_fma_f32 v38, -v42, v44, 1.0
	v_cvt_f32_u32_e32 v43, s33
	v_fmac_f32_e32 v44, v38, v44
	v_div_scale_f32 v38, vcc, v45, s74, v45
	v_mul_f32_e32 v40, v38, v44
	v_fma_f32 v41, -v42, v40, v38
	v_fmac_f32_e32 v40, v41, v44
	v_div_scale_f32 v41, s[10:11], s74, s74, v43
	v_fma_f32 v38, -v42, v40, v38
	v_rcp_f32_e32 v42, v41
	v_div_fmas_f32 v38, v38, v44, v40
	v_div_fixup_f32 v38, v38, s74, v45
	v_fmamk_f32 v89, v38, 0xc1447cbd, v168
	v_fma_f32 v38, -v41, v42, 1.0
	v_fmac_f32_e32 v42, v38, v42
	v_div_scale_f32 v38, vcc, v43, s74, v43
	v_cvt_f32_u32_e32 v45, s80
	v_mul_f32_e32 v40, v38, v42
	v_fma_f32 v44, -v41, v40, v38
	v_fmac_f32_e32 v40, v44, v42
	v_fma_f32 v38, -v41, v40, v38
	v_div_scale_f32 v41, s[10:11], s74, s74, v45
	v_rcp_f32_e32 v44, v41
	v_div_fmas_f32 v38, v38, v42, v40
	v_div_fixup_f32 v38, v38, s74, v43
	v_fmamk_f32 v90, v38, 0xc1447cbd, v168
	v_fma_f32 v38, -v41, v44, 1.0
	v_fmac_f32_e32 v44, v38, v44
	v_div_scale_f32 v38, vcc, v45, s74, v45
	v_mul_f32_e32 v40, v38, v44
	v_fma_f32 v42, -v41, v40, v38
	v_fmac_f32_e32 v40, v42, v44
	v_fma_f32 v38, -v41, v40, v38
	v_div_scale_f32 v41, s[10:11], v39, v39, s75
	v_rcp_f32_e32 v42, v41
	v_div_fmas_f32 v38, v38, v44, v40
	v_div_fixup_f32 v38, v38, s74, v45
	v_fmamk_f32 v91, v38, 0xc1447cbd, v168
	v_fma_f32 v38, -v41, v42, 1.0
	v_fmac_f32_e32 v42, v38, v42
	v_div_scale_f32 v38, vcc, s75, v39, s75
	v_mul_f32_e32 v40, v38, v42
	v_fma_f32 v43, -v41, v40, v38
	v_fmac_f32_e32 v40, v43, v42
	v_fma_f32 v38, -v41, v40, v38
	v_div_fmas_f32 v38, v38, v42, v40
	v_div_fixup_f32 v92, v38, v39, s75
	v_cvt_pk_bf16_f32 v38, v36, s0
	v_lshlrev_b32_e32 v38, 16, v38
	v_sub_f32_e32 v39, v36, v38
	v_cvt_pk_bf16_f32 v36, v35, s0
	v_lshlrev_b32_e32 v36, 16, v36
	v_sub_f32_e32 v40, v35, v36
	v_cvt_pk_bf16_f32 v35, v34, s0
	v_lshlrev_b32_e32 v35, 16, v35
	v_sub_f32_e32 v41, v34, v35
	v_cvt_pk_bf16_f32 v34, v33, s0
	v_lshlrev_b32_e32 v34, 16, v34
	v_sub_f32_e32 v42, v33, v34
	v_cvt_pk_bf16_f32 v33, v32, s0
	v_lshlrev_b32_e32 v33, 16, v33
	v_sub_f32_e32 v43, v32, v33
	v_cvt_pk_bf16_f32 v32, v31, s0
	v_lshlrev_b32_e32 v32, 16, v32
	v_sub_f32_e32 v44, v31, v32
	v_cvt_pk_bf16_f32 v31, v30, s0
	v_lshlrev_b32_e32 v31, 16, v31
	v_sub_f32_e32 v45, v30, v31
	v_cvt_pk_bf16_f32 v30, v37, s0
	v_lshlrev_b32_e32 v46, 16, v30
	s_and_b64 s[10:11], s[30:31], exec
	v_cvt_pk_bf16_f32 v30, v31, v32
	v_cvt_pk_bf16_f32 v31, v33, v34
	v_cvt_pk_bf16_f32 v33, v38, v46
	v_cvt_pk_bf16_f32 v38, v17, s0
	s_cselect_b32 s34, s76, 0x1a80000
	v_cvt_pk_bf16_f32 v32, v35, v36
	v_cvt_pk_bf16_f32 v36, v41, v40
	v_lshlrev_b32_e32 v41, 16, v38
	s_add_u32 s14, s66, s34
	v_cvt_pk_bf16_f32 v34, v45, v44
	v_sub_f32_e32 v45, v17, v41
	v_cvt_pk_bf16_f32 v17, v16, s0
	s_addc_u32 s15, s67, 0
	s_lshl_b32 s20, s46, 7
	v_lshlrev_b32_e32 v40, 16, v17
	s_add_u32 s16, s14, s20
	v_sub_f32_e32 v44, v16, v40
	v_cvt_pk_bf16_f32 v16, v15, s0
	s_addc_u32 s17, s15, 0
	s_ashr_i32 s13, s12, 31
	v_cvt_pk_bf16_f32 v35, v43, v42
	v_lshlrev_b32_e32 v42, 16, v16
	s_lshl_b64 s[10:11], s[12:13], 12
	v_sub_f32_e32 v37, v37, v46
	v_sub_f32_e32 v46, v15, v42
	v_cvt_pk_bf16_f32 v15, v14, s0
	s_add_u32 s14, s14, s10
	v_lshlrev_b32_e32 v43, 16, v15
	s_addc_u32 s15, s15, s11
	v_sub_f32_e32 v47, v14, v43
	v_cvt_pk_bf16_f32 v14, v13, s0
	s_add_u32 s16, s16, s10
	v_lshlrev_b32_e32 v48, 16, v14
	s_addc_u32 s17, s17, s11
	v_lshl_add_u64 v[14:15], s[14:15], 0, v[106:107]
	s_add_i32 s13, s37, 0x1000
	s_mov_b32 m0, s37
	v_lshl_add_u64 v[16:17], s[16:17], 0, v[106:107]
	global_load_lds_dwordx4 v[14:15], off
	s_mov_b32 m0, s13
	s_add_i32 s38, s37, 0x400
	v_cvt_pk_bf16_f32 v37, v39, v37
	global_load_lds_dwordx4 v[16:17], off
	v_lshl_add_u64 v[38:39], v[14:15], 0, s[24:25]
	s_mov_b32 m0, s38
	s_add_i32 s39, s37, 0x1400
	global_load_lds_dwordx4 v[38:39], off
	v_lshl_add_u64 v[38:39], v[16:17], 0, s[24:25]
	s_mov_b32 m0, s39
	s_add_i32 s40, s37, 0x800
	global_load_lds_dwordx4 v[38:39], off
	v_lshl_add_u64 v[38:39], v[14:15], 0, s[26:27]
	s_mov_b32 m0, s40
	s_add_i32 s41, s37, 0x1800
	global_load_lds_dwordx4 v[38:39], off
	v_lshl_add_u64 v[38:39], v[16:17], 0, s[26:27]
	s_mov_b32 m0, s41
	s_add_i32 s44, s37, 0xc00
	global_load_lds_dwordx4 v[38:39], off
	v_lshl_add_u64 v[14:15], v[14:15], 0, s[28:29]
	s_mov_b32 m0, s44
	s_add_i32 s45, s37, 0x1c00
	global_load_lds_dwordx4 v[14:15], off
	v_lshl_add_u64 v[14:15], v[16:17], 0, s[28:29]
	s_mov_b32 m0, s45
	v_cvt_pk_bf16_f32 v16, v12, s0
	global_load_lds_dwordx4 v[14:15], off
	v_cvt_pk_bf16_f32 v14, v11, s0
	v_cvt_pk_bf16_f32 v15, v10, s0
	s_and_b64 s[14:15], s[30:31], exec
	v_lshlrev_b32_e32 v14, 16, v14
	v_lshlrev_b32_e32 v15, 16, v15
	v_lshlrev_b32_e32 v16, 16, v16
	s_cselect_b32 s14, 10, 14
	s_lshl_b32 s17, s12, 6
	s_lshl_b32 s35, s46, 1
	v_sub_f32_e32 v10, v10, v15
	v_sub_f32_e32 v12, v12, v16
	v_cvt_pk_bf16_f32 v38, v15, v14
	v_cvt_pk_bf16_f32 v41, v41, v16
	v_cvt_pk_bf16_f32 v15, v3, s0
	v_cvt_pk_bf16_f32 v16, v2, s0
	s_lshl_b32 s15, 1, s14
	s_lshl_b32 s16, 2, s14
	s_lshl_b32 s14, 3, s14
	s_add_i32 s17, s35, s17
	v_lshlrev_b32_e32 v15, 16, v15
	v_lshlrev_b32_e32 v16, 16, v16
	s_add_i32 s35, s17, s14
	v_sub_f32_e32 v13, v13, v48
	v_sub_f32_e32 v11, v11, v14
	v_sub_f32_e32 v3, v3, v15
	v_sub_f32_e32 v2, v2, v16
	v_add_u32_e32 v93, s35, v165
	s_add_i32 s35, s17, s16
	v_cvt_pk_bf16_f32 v39, v48, v43
	v_cvt_pk_bf16_f32 v40, v42, v40
	v_cvt_pk_bf16_f32 v42, v10, v11
	v_cvt_pk_bf16_f32 v43, v13, v47
	v_cvt_pk_bf16_f32 v45, v45, v12
	v_cvt_pk_bf16_f32 v10, v8, s0
	v_cvt_pk_bf16_f32 v11, v7, s0
	v_cvt_pk_bf16_f32 v12, v6, s0
	v_cvt_pk_bf16_f32 v13, v5, s0
	v_cvt_pk_bf16_f32 v14, v4, s0
	v_cvt_pk_bf16_f32 v17, v9, s0
	v_cvt_pk_bf16_f32 v50, v2, v3
	v_add_u32_e32 v94, s35, v165
	s_add_i32 s35, s17, s15
	v_add_u32_e32 v96, s17, v165
	v_add_u32_e32 v2, s46, v166
	s_lshl_b32 s17, s12, 5
	v_lshlrev_b32_e32 v10, 16, v10
	v_lshlrev_b32_e32 v11, 16, v11
	v_lshlrev_b32_e32 v12, 16, v12
	v_lshlrev_b32_e32 v13, 16, v13
	v_lshlrev_b32_e32 v14, 16, v14
	v_lshlrev_b32_e32 v17, 16, v17
	v_subrev_u32_e32 v2, s17, v2
	s_add_u32 s10, s34, s10
	v_sub_f32_e32 v8, v8, v10
	v_sub_f32_e32 v7, v7, v11
	v_sub_f32_e32 v6, v6, v12
	v_sub_f32_e32 v5, v5, v13
	v_sub_f32_e32 v4, v4, v14
	v_sub_f32_e32 v9, v9, v17
	v_lshlrev_b32_e32 v97, 1, v2
	s_addc_u32 s11, 0, s11
	v_cvt_pk_bf16_f32 v44, v46, v44
	v_cvt_pk_bf16_f32 v46, v16, v15
	v_cvt_pk_bf16_f32 v47, v14, v13
	v_cvt_pk_bf16_f32 v48, v12, v11
	v_cvt_pk_bf16_f32 v49, v10, v17
	v_cvt_pk_bf16_f32 v51, v4, v5
	v_cvt_pk_bf16_f32 v52, v6, v7
	v_cvt_pk_bf16_f32 v53, v8, v9
	v_add_u32_e32 v95, s35, v165
	v_add_u32_e32 v98, s15, v97
	v_add_u32_e32 v99, s16, v97
	v_add_u32_e32 v100, s14, v97
	v_or_b32_e32 v101, s17, v111
	v_lshl_add_u64 v[86:87], v[114:115], 0, s[10:11]
	v_add_u32_e32 v102, s37, v154
	v_add_u32_e32 v103, s37, v156
	v_add_u32_e32 v104, s37, v157
	v_add_u32_e32 v105, s37, v158
	s_branch .LBB0_364

.Lpf_copy:
	v_readfirstlane_b32 s12, v153
	v_and_b32_e32 v2, 63, v1
	s_lshl_b32 s10, s79, 14
	s_lshl_b32 s11, s12, 10
	s_add_i32 s10, s10, s11
	s_add_u32 s14, s66, 0x9c00000
	s_addc_u32 s15, s67, 0
	s_add_u32 s14, s14, s10
	s_addc_u32 s15, s15, 0
	s_add_i32 m0, s11, 0
	v_lshlrev_b32_e32 v2, 4, v2
	global_load_lds_dwordx4 v2, s[14:15]
	s_add_i32 m0, m0, 0x2000
	s_add_u32 s14, s14, 0x2000
	s_addc_u32 s15, s15, 0
	global_load_lds_dwordx4 v2, s[14:15]
	s_add_i32 m0, m0, 0x2000
	s_add_u32 s14, s14, 0x2000
	s_addc_u32 s15, s15, 0
	global_load_lds_dwordx4 v2, s[14:15]
	s_add_i32 m0, m0, 0x2000
	s_add_u32 s14, s14, 0x2000
	s_addc_u32 s15, s15, 0
	global_load_lds_dwordx4 v2, s[14:15]
	s_add_i32 m0, m0, 0x2000
	s_add_u32 s14, s14, 0x2000
	s_addc_u32 s15, s15, 0
	global_load_lds_dwordx4 v2, s[14:15]
	s_add_i32 m0, m0, 0x2000
	s_add_u32 s14, s14, 0x2000
	s_addc_u32 s15, s15, 0
	global_load_lds_dwordx4 v2, s[14:15]
	s_add_i32 m0, m0, 0x2000
	s_add_u32 s14, s14, 0x2000
	s_addc_u32 s15, s15, 0
	global_load_lds_dwordx4 v2, s[14:15]
	s_add_i32 m0, m0, 0x2000
	s_add_u32 s14, s14, 0x2000
	s_addc_u32 s15, s15, 0
	global_load_lds_dwordx4 v2, s[14:15]
